# phase 4 chunk-state GEMM staging: the four serialised K/V loads of each k-step issued together into dead registers with counted vmcnt (on top of the phase 6 / ctx-epilogue de-serialisation)
# speedup vs baseline: 1.0041x; 1.0041x over previous
.LBB0_456:
	s_or_b64 exec, exec, s[38:39]
	s_and_b32 s30, s69, 0xff
	s_mulk_i32 s68, 0x300
	s_lshl_b32 s30, s30, 7
	s_add_i32 s68, s30, s68
	s_mul_i32 s30, s68, 0x4200
	s_add_u32 s38, s42, s30
	s_addc_u32 s39, s43, 0
	s_lshl_b32 s40, s40, 1
	s_add_u32 s38, s38, s40
	s_addc_u32 s39, s39, 0
	s_add_u32 s30, s92, s30
	s_addc_u32 s69, s93, 0
	s_add_u32 s70, s30, s40
	s_addc_u32 s71, s69, 0
	v_lshlrev_b32_e32 v98, 1, v96
	v_lshl_add_u64 v[4:5], s[70:71], 0, v[98:99]
	s_waitcnt lgkmcnt(2)
	v_lshl_add_u64 v[0:1], s[38:39], 0, v[98:99]
	v_lshl_add_u64 v[32:33], v[4:5], 0, v[102:103]
	s_waitcnt lgkmcnt(0)
	s_barrier
	v_lshl_add_u64 v[80:81], v[0:1], 0, v[100:101]
	v_lshl_add_u64 v[34:35], v[4:5], 0, v[104:105]
	v_lshl_add_u64 v[36:37], v[4:5], 0, v[106:107]
	v_lshl_add_u64 v[38:39], v[4:5], 0, v[108:109]
	global_load_dwordx4 v[196:199], v[32:33], off
	global_load_dwordx4 v[188:191], v[34:35], off
	global_load_dwordx4 v[192:195], v[36:37], off
	global_load_dwordx4 v[0:3], v[38:39], off
	s_mov_b32 s30, 0x84000
	v_add_u32_e32 v98, v135, v139
	s_mov_b64 s[38:39], 0x84000
	v_lshl_add_u64 v[84:85], v[80:81], 0, s[38:39]
	s_mov_b64 s[38:39], 0x108000
	v_lshl_add_u64 v[86:87], v[80:81], 0, s[38:39]
	s_mov_b64 s[38:39], 0x18c000
	v_lshl_add_u64 v[120:121], v[80:81], 0, s[38:39]
	s_waitcnt vmcnt(3)
	v_lshlrev_b32_e32 v6, 16, v196
	v_and_b32_e32 v7, 0xffff0000, v196
	v_lshlrev_b32_e32 v10, 16, v197
	v_and_b32_e32 v11, 0xffff0000, v197
	v_lshlrev_b32_e32 v22, 16, v198
	v_and_b32_e32 v23, 0xffff0000, v198
	v_lshlrev_b32_e32 v24, 16, v199
	v_and_b32_e32 v25, 0xffff0000, v199
	s_waitcnt vmcnt(2)
	v_lshlrev_b32_e32 v8, 16, v188
	v_and_b32_e32 v9, 0xffff0000, v188
	v_lshlrev_b32_e32 v26, 16, v189
	v_and_b32_e32 v27, 0xffff0000, v189
	v_lshlrev_b32_e32 v28, 16, v190
	v_and_b32_e32 v29, 0xffff0000, v190
	v_lshlrev_b32_e32 v30, 16, v191
	v_and_b32_e32 v31, 0xffff0000, v191
	s_waitcnt vmcnt(1)
	v_lshlrev_b32_e32 v40, 16, v192
	v_and_b32_e32 v41, 0xffff0000, v192
	v_lshlrev_b32_e32 v42, 16, v193
	v_and_b32_e32 v43, 0xffff0000, v193
	v_lshlrev_b32_e32 v44, 16, v194
	v_and_b32_e32 v45, 0xffff0000, v194
	v_lshlrev_b32_e32 v46, 16, v195
	v_and_b32_e32 v47, 0xffff0000, v195
	ds_read_b128 v[14:17], v127
	ds_read_b128 v[18:21], v127 offset:16
	s_waitcnt lgkmcnt(1)
	v_pk_mul_f32 v[4:5], v[14:15], v[6:7]
	v_pk_mul_f32 v[10:11], v[16:17], v[10:11]
	v_cvt_pk_bf16_f32 v12, v4, v5
	v_pk_mul_f32 v[4:5], v[14:15], v[8:9]
	v_cvt_pk_bf16_f32 v13, v10, v11
	v_pk_mul_f32 v[10:11], v[16:17], v[26:27]
	v_cvt_pk_bf16_f32 v8, v4, v5
	v_pk_mul_f32 v[4:5], v[14:15], v[40:41]
	v_cvt_pk_bf16_f32 v9, v10, v11
	v_pk_mul_f32 v[10:11], v[16:17], v[42:43]
	v_cvt_pk_bf16_f32 v4, v4, v5
	v_cvt_pk_bf16_f32 v5, v10, v11
	s_waitcnt vmcnt(0)
	v_lshlrev_b32_e32 v48, 16, v0
	v_and_b32_e32 v49, 0xffff0000, v0
	v_pk_mul_f32 v[6:7], v[14:15], v[48:49]
	s_nop 0
	v_cvt_pk_bf16_f32 v0, v6, v7
	v_lshlrev_b32_e32 v6, 16, v1
	v_and_b32_e32 v7, 0xffff0000, v1
	v_pk_mul_f32 v[6:7], v[16:17], v[6:7]
	v_lshlrev_b32_e32 v16, 16, v2
	v_cvt_pk_bf16_f32 v1, v6, v7
	s_waitcnt lgkmcnt(0)
	v_pk_mul_f32 v[6:7], v[18:19], v[22:23]
	v_and_b32_e32 v17, 0xffff0000, v2
	v_cvt_pk_bf16_f32 v14, v6, v7
	v_pk_mul_f32 v[6:7], v[18:19], v[28:29]
	v_pk_mul_f32 v[16:17], v[18:19], v[16:17]
	v_cvt_pk_bf16_f32 v10, v6, v7
	v_pk_mul_f32 v[6:7], v[18:19], v[44:45]
	v_pk_mul_f32 v[18:19], v[20:21], v[24:25]
	v_cvt_pk_bf16_f32 v2, v16, v17
	v_lshlrev_b32_e32 v16, 16, v3
	v_and_b32_e32 v17, 0xffff0000, v3
	v_cvt_pk_bf16_f32 v15, v18, v19
	v_pk_mul_f32 v[18:19], v[20:21], v[30:31]
	v_pk_mul_f32 v[16:17], v[20:21], v[16:17]
	v_cvt_pk_bf16_f32 v11, v18, v19
	v_pk_mul_f32 v[18:19], v[20:21], v[46:47]
	v_cvt_pk_bf16_f32 v6, v6, v7
	v_cvt_pk_bf16_f32 v7, v18, v19
	v_cvt_pk_bf16_f32 v3, v16, v17
	global_load_dwordx4 v[16:19], v[80:81], off
	v_add_co_u32_e32 v20, vcc, s30, v80
	s_mov_b32 s30, 0x108000
	s_nop 0
	v_addc_co_u32_e32 v21, vcc, 0, v81, vcc
	global_load_dwordx4 v[20:23], v[20:21], off
	v_add_co_u32_e32 v24, vcc, s30, v80
	s_mov_b32 s30, 0x18c000
	s_nop 0
	v_addc_co_u32_e32 v25, vcc, 0, v81, vcc
	global_load_dwordx4 v[24:27], v[24:25], off
	v_add_co_u32_e32 v28, vcc, s30, v80
	s_add_i32 s30, s41, s67
	s_nop 0
	v_addc_co_u32_e32 v29, vcc, 0, v81, vcc
	global_load_dwordx4 v[28:31], v[28:29], off
	s_barrier
	s_lshl_b64 s[38:39], s[30:31], 15
	s_waitcnt vmcnt(3)
	ds_write_b128 v136, v[16:19]
	ds_write_b128 v136, v[12:15] offset:18432
	s_waitcnt vmcnt(2)
	ds_write_b128 v136, v[20:23] offset:4608
	ds_write_b128 v136, v[8:11] offset:23040
	s_waitcnt vmcnt(1)
	ds_write_b128 v136, v[24:27] offset:9216
	ds_write_b128 v136, v[4:7] offset:27648
	s_waitcnt vmcnt(0)
	ds_write_b128 v136, v[28:31] offset:13824
	ds_write_b128 v136, v[0:3] offset:32256
	s_waitcnt lgkmcnt(0)
	s_barrier
	global_load_dwordx4 v[196:199], v[38:39], off offset:128
	global_load_dwordx4 v[188:191], v[36:37], off offset:128
	global_load_dwordx4 v[192:195], v[34:35], off offset:128
	global_load_dwordx4 v[0:3], v[32:33], off offset:128
	s_waitcnt vmcnt(3)
	v_lshlrev_b32_e32 v4, 16, v199
	v_and_b32_e32 v5, 0xffff0000, v199
	v_lshlrev_b32_e32 v8, 16, v198
	v_and_b32_e32 v9, 0xffff0000, v198
	v_lshlrev_b32_e32 v20, 16, v197
	v_and_b32_e32 v21, 0xffff0000, v197
	v_lshlrev_b32_e32 v22, 16, v196
	v_and_b32_e32 v23, 0xffff0000, v196
	s_waitcnt vmcnt(2)
	v_lshlrev_b32_e32 v6, 16, v191
	v_and_b32_e32 v7, 0xffff0000, v191
	v_lshlrev_b32_e32 v24, 16, v190
	v_and_b32_e32 v25, 0xffff0000, v190
	v_lshlrev_b32_e32 v26, 16, v189
	v_and_b32_e32 v27, 0xffff0000, v189
	v_lshlrev_b32_e32 v28, 16, v188
	v_and_b32_e32 v29, 0xffff0000, v188
	s_waitcnt vmcnt(1)
	v_lshlrev_b32_e32 v10, 16, v195
	v_and_b32_e32 v11, 0xffff0000, v195
	v_lshlrev_b32_e32 v30, 16, v194
	v_and_b32_e32 v31, 0xffff0000, v194
	v_lshlrev_b32_e32 v34, 16, v193
	v_and_b32_e32 v35, 0xffff0000, v193
	v_lshlrev_b32_e32 v36, 16, v192
	v_and_b32_e32 v37, 0xffff0000, v192
	ds_read_b128 v[16:19], v138
	ds_read_b128 v[12:15], v138 offset:16
	s_waitcnt lgkmcnt(0)
	v_pk_mul_f32 v[4:5], v[14:15], v[4:5]
	v_pk_mul_f32 v[8:9], v[12:13], v[8:9]
	s_waitcnt vmcnt(0)
	v_lshlrev_b32_e32 v32, 16, v3
	v_and_b32_e32 v33, 0xffff0000, v3
	v_cvt_pk_bf16_f32 v3, v4, v5
	v_pk_mul_f32 v[4:5], v[14:15], v[6:7]
	s_nop 0
	v_cvt_pk_bf16_f32 v7, v4, v5
	v_pk_mul_f32 v[4:5], v[14:15], v[10:11]
	s_nop 0
	v_cvt_pk_bf16_f32 v11, v4, v5
	v_pk_mul_f32 v[4:5], v[14:15], v[32:33]
	s_nop 0
	v_cvt_pk_bf16_f32 v15, v4, v5
	v_lshlrev_b32_e32 v4, 16, v2
	v_and_b32_e32 v5, 0xffff0000, v2
	v_cvt_pk_bf16_f32 v2, v8, v9
	v_pk_mul_f32 v[8:9], v[12:13], v[24:25]
	v_pk_mul_f32 v[4:5], v[12:13], v[4:5]
	v_cvt_pk_bf16_f32 v6, v8, v9
	v_pk_mul_f32 v[8:9], v[12:13], v[30:31]
	v_cvt_pk_bf16_f32 v14, v4, v5
	v_lshlrev_b32_e32 v12, 16, v1
	v_and_b32_e32 v13, 0xffff0000, v1
	v_pk_mul_f32 v[4:5], v[18:19], v[20:21]
	v_pk_mul_f32 v[20:21], v[16:17], v[22:23]
	v_cvt_pk_bf16_f32 v10, v8, v9
	v_cvt_pk_bf16_f32 v1, v4, v5
	v_pk_mul_f32 v[4:5], v[18:19], v[26:27]
	v_pk_mul_f32 v[8:9], v[18:19], v[34:35]
	v_pk_mul_f32 v[12:13], v[18:19], v[12:13]
	v_lshlrev_b32_e32 v18, 16, v0
	v_and_b32_e32 v19, 0xffff0000, v0
	v_cvt_pk_bf16_f32 v0, v20, v21
	v_pk_mul_f32 v[20:21], v[16:17], v[28:29]
	v_cvt_pk_bf16_f32 v5, v4, v5
	v_cvt_pk_bf16_f32 v4, v20, v21
	v_pk_mul_f32 v[20:21], v[16:17], v[36:37]
	v_pk_mul_f32 v[16:17], v[16:17], v[18:19]
	v_cvt_pk_bf16_f32 v9, v8, v9
	v_cvt_pk_bf16_f32 v13, v12, v13
	v_cvt_pk_bf16_f32 v8, v20, v21
	v_cvt_pk_bf16_f32 v12, v16, v17
	ds_read_b128 v[20:23], v98
	ds_read_b128 v[16:19], v98 offset:2304
	ds_read_b128 v[24:27], v140 offset:18432
	ds_read_b128 v[28:31], v140 offset:20736
	ds_read_b128 v[32:35], v140 offset:23040
	ds_read_b128 v[36:39], v140 offset:25344
	ds_read_b128 v[40:43], v140 offset:27648
	ds_read_b128 v[44:47], v140 offset:29952
	ds_read_b128 v[48:51], v140 offset:32256
	ds_read_b128 v[52:55], v140 offset:34560
	s_waitcnt lgkmcnt(2)
	v_mfma_f32_16x16x32_bf16 v[76:79], v[44:47], v[20:23], 0
	s_waitcnt lgkmcnt(1)
	v_mfma_f32_16x16x32_bf16 v[88:91], v[48:51], v[20:23], 0
	s_waitcnt lgkmcnt(0)
	v_mfma_f32_16x16x32_bf16 v[92:95], v[52:55], v[20:23], 0
	v_mfma_f32_16x16x32_bf16 v[198:201], v[44:47], v[16:19], 0
	v_mfma_f32_16x16x32_bf16 v[202:205], v[48:51], v[16:19], 0
	v_mfma_f32_16x16x32_bf16 v[206:209], v[52:55], v[16:19], 0
	ds_read_b128 v[44:47], v98 offset:64
	ds_read_b128 v[210:213], v98 offset:2368
	ds_read_b128 v[48:51], v140 offset:18496
	ds_read_b128 v[52:55], v140 offset:20800
	ds_read_b128 v[214:217], v140 offset:23104
	ds_read_b128 v[218:221], v140 offset:25408
	ds_read_b128 v[222:225], v140 offset:27712
	ds_read_b128 v[226:229], v140 offset:30016
	ds_read_b128 v[230:233], v140 offset:32320
	ds_read_b128 v[234:237], v140 offset:34624
	v_mfma_f32_16x16x32_bf16 v[56:59], v[24:27], v[20:23], 0
	v_mfma_f32_16x16x32_bf16 v[60:63], v[28:31], v[20:23], 0
	v_mfma_f32_16x16x32_bf16 v[64:67], v[32:35], v[20:23], 0
	v_mfma_f32_16x16x32_bf16 v[68:71], v[36:39], v[20:23], 0
	v_mfma_f32_16x16x32_bf16 v[72:75], v[40:43], v[20:23], 0
	v_mfma_f32_16x16x32_bf16 v[122:125], v[24:27], v[16:19], 0
	v_mfma_f32_16x16x32_bf16 v[154:157], v[28:31], v[16:19], 0
	v_mfma_f32_16x16x32_bf16 v[186:189], v[32:35], v[16:19], 0
	v_mfma_f32_16x16x32_bf16 v[190:193], v[36:39], v[16:19], 0
	v_mfma_f32_16x16x32_bf16 v[194:197], v[40:43], v[16:19], 0
	s_waitcnt lgkmcnt(7)
	v_mfma_f32_16x16x32_bf16 v[16:19], v[48:51], v[44:47], v[56:59]
	s_waitcnt lgkmcnt(6)
	v_mfma_f32_16x16x32_bf16 v[20:23], v[52:55], v[44:47], v[60:63]
	s_waitcnt lgkmcnt(5)
	v_mfma_f32_16x16x32_bf16 v[24:27], v[214:217], v[44:47], v[64:67]
	s_waitcnt lgkmcnt(4)
	v_mfma_f32_16x16x32_bf16 v[28:31], v[218:221], v[44:47], v[68:71]
	s_waitcnt lgkmcnt(3)
	v_mfma_f32_16x16x32_bf16 v[32:35], v[222:225], v[44:47], v[72:75]
	s_waitcnt lgkmcnt(2)
	v_mfma_f32_16x16x32_bf16 v[36:39], v[226:229], v[44:47], v[76:79]
	s_waitcnt lgkmcnt(1)
	v_mfma_f32_16x16x32_bf16 v[40:43], v[230:233], v[44:47], v[88:91]
	s_waitcnt lgkmcnt(0)
	v_mfma_f32_16x16x32_bf16 v[44:47], v[234:237], v[44:47], v[92:95]
	global_load_dwordx4 v[80:83], v[80:81], off offset:128
	s_nop 1
	global_load_dwordx4 v[92:95], v[84:85], off offset:128
	global_load_dwordx4 v[88:91], v[86:87], off offset:128
	s_nop 0
	global_load_dwordx4 v[84:87], v[120:121], off offset:128
	s_barrier
	v_mfma_f32_16x16x32_bf16 v[48:51], v[48:51], v[210:213], v[122:125]
	s_waitcnt vmcnt(3)
	ds_write_b128 v136, v[80:83]
	ds_write_b128 v136, v[12:15] offset:18432
	s_waitcnt vmcnt(2)
	ds_write_b128 v136, v[92:95] offset:4608
	ds_write_b128 v136, v[8:11] offset:23040
	s_waitcnt vmcnt(1)
	ds_write_b128 v136, v[88:91] offset:9216
	ds_write_b128 v136, v[4:7] offset:27648
	s_waitcnt vmcnt(0)
	ds_write_b128 v136, v[84:87] offset:13824
	ds_write_b128 v136, v[0:3] offset:32256
	v_mfma_f32_16x16x32_bf16 v[52:55], v[52:55], v[210:213], v[154:157]
	s_waitcnt lgkmcnt(0)
	s_barrier
	ds_read_b128 v[0:3], v140 offset:34560
	ds_read_b128 v[4:7], v140 offset:32256
	ds_read_b128 v[8:11], v140 offset:29952
	ds_read_b128 v[12:15], v140 offset:27648
	ds_read_b128 v[80:83], v140 offset:25344
	ds_read_b128 v[84:87], v140 offset:23040
	ds_read_b128 v[88:91], v140 offset:20736
	ds_read_b128 v[92:95], v140 offset:18432
	ds_read_b128 v[120:123], v98 offset:2304
	ds_read_b128 v[154:157], v98
	v_mfma_f32_16x16x32_bf16 v[56:59], v[214:217], v[210:213], v[186:189]
	v_mfma_f32_16x16x32_bf16 v[60:63], v[218:221], v[210:213], v[190:193]
	v_mfma_f32_16x16x32_bf16 v[64:67], v[222:225], v[210:213], v[194:197]
	v_mfma_f32_16x16x32_bf16 v[68:71], v[226:229], v[210:213], v[198:201]
	v_mfma_f32_16x16x32_bf16 v[72:75], v[230:233], v[210:213], v[202:205]
	v_mfma_f32_16x16x32_bf16 v[76:79], v[234:237], v[210:213], v[206:209]
	s_waitcnt lgkmcnt(0)
	v_mfma_f32_16x16x32_bf16 v[16:19], v[92:95], v[154:157], v[16:19]
	v_mfma_f32_16x16x32_bf16 v[20:23], v[88:91], v[154:157], v[20:23]
	v_mfma_f32_16x16x32_bf16 v[24:27], v[84:87], v[154:157], v[24:27]
	v_mfma_f32_16x16x32_bf16 v[28:31], v[80:83], v[154:157], v[28:31]
	v_mfma_f32_16x16x32_bf16 v[32:35], v[12:15], v[154:157], v[32:35]
	v_mfma_f32_16x16x32_bf16 v[36:39], v[8:11], v[154:157], v[36:39]
	v_mfma_f32_16x16x32_bf16 v[40:43], v[4:7], v[154:157], v[40:43]
	v_mfma_f32_16x16x32_bf16 v[44:47], v[0:3], v[154:157], v[44:47]
	v_mfma_f32_16x16x32_bf16 v[48:51], v[92:95], v[120:123], v[48:51]
	v_mfma_f32_16x16x32_bf16 v[52:55], v[88:91], v[120:123], v[52:55]
	v_mfma_f32_16x16x32_bf16 v[56:59], v[84:87], v[120:123], v[56:59]
	v_mfma_f32_16x16x32_bf16 v[60:63], v[80:83], v[120:123], v[60:63]
	v_mfma_f32_16x16x32_bf16 v[12:15], v[12:15], v[120:123], v[64:67]
	v_mfma_f32_16x16x32_bf16 v[8:11], v[8:11], v[120:123], v[68:71]
	v_mfma_f32_16x16x32_bf16 v[4:7], v[4:7], v[120:123], v[72:75]
	v_mfma_f32_16x16x32_bf16 v[0:3], v[0:3], v[120:123], v[76:79]
	ds_read_b128 v[64:67], v98 offset:64
	ds_read_b128 v[68:71], v98 offset:2368
	ds_read_b128 v[72:75], v140 offset:18496
	ds_read_b128 v[76:79], v140 offset:20800
	ds_read_b128 v[80:83], v140 offset:23104
	ds_read_b128 v[84:87], v140 offset:25408
	ds_read_b128 v[88:91], v140 offset:27712
	ds_read_b128 v[92:95], v140 offset:30016
	ds_read_b128 v[120:123], v140 offset:32320
	ds_read_b128 v[154:157], v140 offset:34624
	s_waitcnt lgkmcnt(7)
	v_mfma_f32_16x16x32_bf16 v[16:19], v[72:75], v[64:67], v[16:19]
	s_waitcnt lgkmcnt(6)
	v_mfma_f32_16x16x32_bf16 v[20:23], v[76:79], v[64:67], v[20:23]
	s_waitcnt lgkmcnt(5)
	v_mfma_f32_16x16x32_bf16 v[24:27], v[80:83], v[64:67], v[24:27]
	s_nop 3
	v_cvt_pk_bf16_f32 v16, v16, v17
	v_cvt_pk_bf16_f32 v17, v18, v19
	v_cvt_pk_bf16_f32 v18, v20, v21
	s_waitcnt lgkmcnt(4)
	v_mfma_f32_16x16x32_bf16 v[28:31], v[84:87], v[64:67], v[28:31]
	v_cvt_pk_bf16_f32 v19, v22, v23
	s_waitcnt lgkmcnt(3)
	v_mfma_f32_16x16x32_bf16 v[32:35], v[88:91], v[64:67], v[32:35]
	s_waitcnt lgkmcnt(2)
	v_mfma_f32_16x16x32_bf16 v[36:39], v[92:95], v[64:67], v[36:39]
	s_waitcnt lgkmcnt(1)
	v_mfma_f32_16x16x32_bf16 v[40:43], v[120:123], v[64:67], v[40:43]
	s_waitcnt lgkmcnt(0)
	v_mfma_f32_16x16x32_bf16 v[44:47], v[154:157], v[64:67], v[44:47]
	v_lshl_add_u64 v[64:65], v[112:113], 0, s[38:39]
	global_store_dwordx4 v[64:65], v[16:19], off
	s_movk_i32 s38, 0x1000
	v_mfma_f32_16x16x32_bf16 v[48:51], v[72:75], v[68:71], v[48:51]
	v_cvt_pk_bf16_f32 v16, v24, v25
	v_cvt_pk_bf16_f32 v17, v26, v27
	v_cvt_pk_bf16_f32 v18, v28, v29
	v_mfma_f32_16x16x32_bf16 v[52:55], v[76:79], v[68:71], v[52:55]
	v_cvt_pk_bf16_f32 v19, v30, v31
	global_store_dwordx4 v[64:65], v[16:19], off offset:64
	v_add_co_u32_e32 v20, vcc, s38, v64
	v_mfma_f32_16x16x32_bf16 v[56:59], v[80:83], v[68:71], v[56:59]
	v_cvt_pk_bf16_f32 v16, v32, v33
	v_cvt_pk_bf16_f32 v17, v34, v35
	v_cvt_pk_bf16_f32 v18, v36, v37
	v_mfma_f32_16x16x32_bf16 v[60:63], v[84:87], v[68:71], v[60:63]
	v_cvt_pk_bf16_f32 v19, v38, v39
	global_store_dwordx4 v[64:65], v[16:19], off offset:128
	v_addc_co_u32_e32 v21, vcc, 0, v65, vcc
	v_mfma_f32_16x16x32_bf16 v[12:15], v[88:91], v[68:71], v[12:15]
	v_cvt_pk_bf16_f32 v16, v40, v41
	v_cvt_pk_bf16_f32 v17, v42, v43
	v_cvt_pk_bf16_f32 v18, v44, v45
	v_mfma_f32_16x16x32_bf16 v[8:11], v[92:95], v[68:71], v[8:11]
	v_cvt_pk_bf16_f32 v19, v46, v47
	global_store_dwordx4 v[64:65], v[16:19], off offset:192
	s_nop 1
	v_cvt_pk_bf16_f32 v12, v12, v13
	v_mfma_f32_16x16x32_bf16 v[4:7], v[120:123], v[68:71], v[4:7]
	v_cvt_pk_bf16_f32 v16, v48, v49
	v_cvt_pk_bf16_f32 v17, v50, v51
	v_cvt_pk_bf16_f32 v18, v52, v53
	v_mfma_f32_16x16x32_bf16 v[0:3], v[154:157], v[68:71], v[0:3]
	v_cvt_pk_bf16_f32 v19, v54, v55
	global_store_dwordx4 v[20:21], v[16:19], off
	v_cvt_pk_bf16_f32 v13, v14, v15
	v_cvt_pk_bf16_f32 v14, v8, v9
	v_cvt_pk_bf16_f32 v16, v56, v57
	v_cvt_pk_bf16_f32 v17, v58, v59
	v_cvt_pk_bf16_f32 v18, v60, v61
	v_cvt_pk_bf16_f32 v19, v62, v63
	v_cvt_pk_bf16_f32 v15, v10, v11
	v_cvt_pk_bf16_f32 v4, v4, v5
	v_cvt_pk_bf16_f32 v5, v6, v7
	v_cvt_pk_bf16_f32 v6, v0, v1
	v_cvt_pk_bf16_f32 v7, v2, v3
	global_store_dwordx4 v[20:21], v[16:19], off offset:64
	global_store_dwordx4 v[20:21], v[12:15], off offset:128
	global_store_dwordx4 v[20:21], v[4:7], off offset:192
	s_and_saveexec_b64 s[38:39], s[2:3]
	s_cbranch_execz .LBB0_458
	v_mov_b32_e32 v16, v144
	v_mov_b64_e32 v[0:1], s[92:93]
	v_add_u32_e32 v2, s68, v16
	v_mad_i64_i32 v[0:1], s[68:69], v2, s45, v[0:1]
	s_mov_b32 s41, s31
	v_lshl_add_u64 v[18:19], v[0:1], 0, s[40:41]
	global_load_dwordx4 v[0:3], v[18:19], off offset:48
	global_load_dwordx4 v[4:7], v[18:19], off offset:32
	global_load_dwordx4 v[8:11], v[18:19], off offset:16
	global_load_dwordx4 v[12:15], v[18:19], off
	v_mov_b32_e32 v20, s44
	ds_read_b128 v[20:23], v20
	v_mov_b32_e32 v32, s58
	s_lshl_b32 s30, s30, 9
	s_add_u32 s40, s33, s30
	s_addc_u32 s41, s37, 0
	s_waitcnt vmcnt(0)
	v_lshlrev_b32_e32 v17, 16, v12
	v_and_b32_e32 v12, 0xffff0000, v12
	s_waitcnt lgkmcnt(0)
	v_mul_f32_e32 v12, v21, v12
	v_fmac_f32_e32 v12, v20, v17
	v_lshlrev_b32_e32 v17, 16, v13
	v_fmac_f32_e32 v12, v22, v17
	v_and_b32_e32 v13, 0xffff0000, v13
	v_mov_b32_e32 v17, s51
	v_fmac_f32_e32 v12, v23, v13
	ds_read_b128 v[20:23], v17
	v_lshlrev_b32_e32 v13, 16, v14
	s_waitcnt lgkmcnt(0)
	v_fmac_f32_e32 v12, v20, v13
	v_and_b32_e32 v13, 0xffff0000, v14
	v_fmac_f32_e32 v12, v21, v13
	v_lshlrev_b32_e32 v13, 16, v15
	v_fmac_f32_e32 v12, v22, v13
	v_and_b32_e32 v13, 0xffff0000, v15
	v_fmac_f32_e32 v12, v23, v13
	v_add_f32_e32 v17, 0, v12
	v_mov_b32_e32 v12, s52
	ds_read_b128 v[12:15], v12
	v_lshlrev_b32_e32 v20, 16, v8
	v_and_b32_e32 v8, 0xffff0000, v8
	s_waitcnt lgkmcnt(0)
	v_mul_f32_e32 v8, v13, v8
	v_fmac_f32_e32 v8, v12, v20
	v_lshlrev_b32_e32 v12, 16, v9
	v_fmac_f32_e32 v8, v14, v12
	v_and_b32_e32 v9, 0xffff0000, v9
	v_mov_b32_e32 v12, s53
	v_fmac_f32_e32 v8, v15, v9
	ds_read_b128 v[12:15], v12
	v_lshlrev_b32_e32 v9, 16, v10
	s_waitcnt lgkmcnt(0)
	v_fmac_f32_e32 v8, v12, v9
	v_and_b32_e32 v9, 0xffff0000, v10
	v_fmac_f32_e32 v8, v13, v9
	v_lshlrev_b32_e32 v9, 16, v11
	v_fmac_f32_e32 v8, v14, v9
	v_and_b32_e32 v9, 0xffff0000, v11
	v_fmac_f32_e32 v8, v15, v9
	v_add_f32_e32 v12, v17, v8
	v_mov_b32_e32 v8, s54
	ds_read_b128 v[8:11], v8
	v_lshlrev_b32_e32 v13, 16, v4
	v_and_b32_e32 v4, 0xffff0000, v4
	s_waitcnt lgkmcnt(0)
	v_mul_f32_e32 v4, v9, v4
	v_fmac_f32_e32 v4, v8, v13
	v_lshlrev_b32_e32 v8, 16, v5
	v_fmac_f32_e32 v4, v10, v8
	v_and_b32_e32 v5, 0xffff0000, v5
	v_mov_b32_e32 v8, s55
	v_fmac_f32_e32 v4, v11, v5
	ds_read_b128 v[8:11], v8
	v_lshlrev_b32_e32 v5, 16, v6
	s_waitcnt lgkmcnt(0)
	v_fmac_f32_e32 v4, v8, v5
	v_and_b32_e32 v5, 0xffff0000, v6
	v_fmac_f32_e32 v4, v9, v5
	v_lshlrev_b32_e32 v5, 16, v7
	v_fmac_f32_e32 v4, v10, v5
	v_and_b32_e32 v5, 0xffff0000, v7
	v_fmac_f32_e32 v4, v11, v5
	v_add_f32_e32 v8, v12, v4
	v_mov_b32_e32 v4, s56
	ds_read_b128 v[4:7], v4
	v_lshlrev_b32_e32 v9, 16, v0
	v_and_b32_e32 v0, 0xffff0000, v0
	s_waitcnt lgkmcnt(0)
	v_mul_f32_e32 v0, v5, v0
	v_fmac_f32_e32 v0, v4, v9
	v_lshlrev_b32_e32 v4, 16, v1
	v_fmac_f32_e32 v0, v6, v4
	v_and_b32_e32 v1, 0xffff0000, v1
	v_mov_b32_e32 v4, s57
	v_fmac_f32_e32 v0, v7, v1
	ds_read_b128 v[4:7], v4
	v_lshlrev_b32_e32 v1, 16, v2
	s_waitcnt lgkmcnt(0)
	v_fmac_f32_e32 v0, v4, v1
	v_and_b32_e32 v1, 0xffff0000, v2
	v_fmac_f32_e32 v0, v5, v1
	v_lshlrev_b32_e32 v1, 16, v3
	v_fmac_f32_e32 v0, v6, v1
	v_and_b32_e32 v1, 0xffff0000, v3
	v_fmac_f32_e32 v0, v7, v1
	v_add_f32_e32 v17, v8, v0
	global_load_dwordx4 v[0:3], v[18:19], off offset:112
	global_load_dwordx4 v[4:7], v[18:19], off offset:96
	global_load_dwordx4 v[8:11], v[18:19], off offset:80
	global_load_dwordx4 v[12:15], v[18:19], off offset:64
	ds_read_b128 v[20:23], v32
	ds_read_b128 v[24:27], v32 offset:16
	ds_read_b128 v[28:31], v32 offset:32
	ds_read_b128 v[32:35], v32 offset:48
	s_waitcnt lgkmcnt(3)
	v_mov_b32_e32 v38, v20
	s_waitcnt lgkmcnt(1)
	v_mov_b32_e32 v39, v28
	v_mov_b32_e32 v28, v21
	s_waitcnt vmcnt(1)
	v_and_b32_e32 v41, 0xffff0000, v8
	s_waitcnt vmcnt(0)
	v_and_b32_e32 v40, 0xffff0000, v12
	v_lshlrev_b32_e32 v37, 16, v8
	v_lshlrev_b32_e32 v36, 16, v12
	v_pk_mul_f32 v[20:21], v[28:29], v[40:41]
	v_lshlrev_b32_e32 v29, 16, v9
	v_pk_fma_f32 v[20:21], v[38:39], v[36:37], v[20:21]
	v_lshlrev_b32_e32 v28, 16, v13
	v_mov_b32_e32 v36, v22
	v_mov_b32_e32 v37, v30
	v_pk_fma_f32 v[20:21], v[36:37], v[28:29], v[20:21]
	v_and_b32_e32 v9, 0xffff0000, v9
	v_and_b32_e32 v8, 0xffff0000, v13
	v_mov_b32_e32 v30, v23
	v_pk_fma_f32 v[8:9], v[30:31], v[8:9], v[20:21]
	v_lshlrev_b32_e32 v13, 16, v10
	v_lshlrev_b32_e32 v12, 16, v14
	v_mov_b32_e32 v20, v24
	s_waitcnt lgkmcnt(0)
	v_mov_b32_e32 v21, v32
	v_pk_fma_f32 v[8:9], v[20:21], v[12:13], v[8:9]
	v_and_b32_e32 v13, 0xffff0000, v10
	v_and_b32_e32 v12, 0xffff0000, v14
	v_mov_b32_e32 v32, v25
	v_pk_fma_f32 v[8:9], v[32:33], v[12:13], v[8:9]
	v_lshlrev_b32_e32 v13, 16, v11
	v_lshlrev_b32_e32 v12, 16, v15
	v_mov_b32_e32 v20, v26
	v_mov_b32_e32 v21, v34
	v_pk_fma_f32 v[8:9], v[20:21], v[12:13], v[8:9]
	v_and_b32_e32 v11, 0xffff0000, v11
	v_and_b32_e32 v10, 0xffff0000, v15
	v_mov_b32_e32 v34, v27
	v_pk_fma_f32 v[8:9], v[34:35], v[10:11], v[8:9]
	v_mov_b32_e32 v24, s59
	v_add_f32_e32 v8, v17, v8
	v_add_f32_e32 v17, v8, v9
	ds_read_b128 v[8:11], v24
	ds_read_b128 v[12:15], v24 offset:16
	ds_read_b128 v[20:23], v24 offset:32
	ds_read_b128 v[24:27], v24 offset:48
	v_and_b32_e32 v33, 0xffff0000, v0
	v_and_b32_e32 v32, 0xffff0000, v4
	v_lshlrev_b32_e32 v29, 16, v0
	s_waitcnt lgkmcnt(1)
	v_mov_b32_e32 v31, v20
	v_mov_b32_e32 v20, v9
	v_lshlrev_b32_e32 v28, 16, v4
	v_mov_b32_e32 v30, v8
	v_pk_mul_f32 v[8:9], v[20:21], v[32:33]
	v_lshlrev_b32_e32 v21, 16, v1
	v_pk_fma_f32 v[8:9], v[30:31], v[28:29], v[8:9]
	v_lshlrev_b32_e32 v20, 16, v5
	v_mov_b32_e32 v28, v10
	v_mov_b32_e32 v29, v22
	v_pk_fma_f32 v[8:9], v[28:29], v[20:21], v[8:9]
	v_and_b32_e32 v1, 0xffff0000, v1
	v_and_b32_e32 v0, 0xffff0000, v5
	v_mov_b32_e32 v22, v11
	v_pk_fma_f32 v[0:1], v[22:23], v[0:1], v[8:9]
	v_lshlrev_b32_e32 v5, 16, v2
	v_lshlrev_b32_e32 v4, 16, v6
	v_mov_b32_e32 v8, v12
	s_waitcnt lgkmcnt(0)
	v_mov_b32_e32 v9, v24
	v_pk_fma_f32 v[0:1], v[8:9], v[4:5], v[0:1]
	v_and_b32_e32 v5, 0xffff0000, v2
	v_and_b32_e32 v4, 0xffff0000, v6
	v_mov_b32_e32 v24, v13
	v_pk_fma_f32 v[0:1], v[24:25], v[4:5], v[0:1]
	v_lshlrev_b32_e32 v5, 16, v3
	v_lshlrev_b32_e32 v4, 16, v7
	v_mov_b32_e32 v8, v14
	v_mov_b32_e32 v9, v26
	v_pk_fma_f32 v[0:1], v[8:9], v[4:5], v[0:1]
	v_and_b32_e32 v3, 0xffff0000, v3
	v_and_b32_e32 v2, 0xffff0000, v7
	v_mov_b32_e32 v26, v15
	v_pk_fma_f32 v[0:1], v[26:27], v[2:3], v[0:1]
	v_mov_b32_e32 v32, s60
	v_add_f32_e32 v0, v17, v0
	v_add_f32_e32 v17, v0, v1
	global_load_dwordx4 v[0:3], v[18:19], off offset:176
	global_load_dwordx4 v[4:7], v[18:19], off offset:160
	global_load_dwordx4 v[8:11], v[18:19], off offset:144
	global_load_dwordx4 v[12:15], v[18:19], off offset:128
	ds_read_b128 v[20:23], v32
	ds_read_b128 v[24:27], v32 offset:16
	ds_read_b128 v[28:31], v32 offset:32
	ds_read_b128 v[32:35], v32 offset:48
	s_waitcnt lgkmcnt(3)
	v_mov_b32_e32 v38, v20
	s_waitcnt lgkmcnt(1)
	v_mov_b32_e32 v39, v28
	v_mov_b32_e32 v28, v21
	s_waitcnt vmcnt(1)
	v_and_b32_e32 v41, 0xffff0000, v8
	s_waitcnt vmcnt(0)
	v_and_b32_e32 v40, 0xffff0000, v12
	v_lshlrev_b32_e32 v37, 16, v8
	v_lshlrev_b32_e32 v36, 16, v12
	v_pk_mul_f32 v[20:21], v[28:29], v[40:41]
	v_lshlrev_b32_e32 v29, 16, v9
	v_pk_fma_f32 v[20:21], v[38:39], v[36:37], v[20:21]
	v_lshlrev_b32_e32 v28, 16, v13
	v_mov_b32_e32 v36, v22
	v_mov_b32_e32 v37, v30
	v_pk_fma_f32 v[20:21], v[36:37], v[28:29], v[20:21]
	v_and_b32_e32 v9, 0xffff0000, v9
	v_and_b32_e32 v8, 0xffff0000, v13
	v_mov_b32_e32 v30, v23
	v_pk_fma_f32 v[8:9], v[30:31], v[8:9], v[20:21]
	v_lshlrev_b32_e32 v13, 16, v10
	v_lshlrev_b32_e32 v12, 16, v14
	v_mov_b32_e32 v20, v24
	s_waitcnt lgkmcnt(0)
	v_mov_b32_e32 v21, v32
	v_pk_fma_f32 v[8:9], v[20:21], v[12:13], v[8:9]
	v_and_b32_e32 v13, 0xffff0000, v10
	v_and_b32_e32 v12, 0xffff0000, v14
	v_mov_b32_e32 v32, v25
	v_pk_fma_f32 v[8:9], v[32:33], v[12:13], v[8:9]
	v_lshlrev_b32_e32 v13, 16, v11
	v_lshlrev_b32_e32 v12, 16, v15
	v_mov_b32_e32 v20, v26
	v_mov_b32_e32 v21, v34
	v_pk_fma_f32 v[8:9], v[20:21], v[12:13], v[8:9]
	v_and_b32_e32 v11, 0xffff0000, v11
	v_and_b32_e32 v10, 0xffff0000, v15
	v_mov_b32_e32 v34, v27
	v_pk_fma_f32 v[8:9], v[34:35], v[10:11], v[8:9]
	v_mov_b32_e32 v24, s61
	v_add_f32_e32 v8, v17, v8
	v_add_f32_e32 v17, v8, v9
	ds_read_b128 v[8:11], v24
	ds_read_b128 v[12:15], v24 offset:16
	ds_read_b128 v[20:23], v24 offset:32
	ds_read_b128 v[24:27], v24 offset:48
	v_and_b32_e32 v33, 0xffff0000, v0
	v_and_b32_e32 v32, 0xffff0000, v4
	v_lshlrev_b32_e32 v29, 16, v0
	s_waitcnt lgkmcnt(1)
	v_mov_b32_e32 v31, v20
	v_mov_b32_e32 v20, v9
	v_lshlrev_b32_e32 v28, 16, v4
	v_mov_b32_e32 v30, v8
	v_pk_mul_f32 v[8:9], v[20:21], v[32:33]
	v_lshlrev_b32_e32 v21, 16, v1
	v_pk_fma_f32 v[8:9], v[30:31], v[28:29], v[8:9]
	v_lshlrev_b32_e32 v20, 16, v5
	v_mov_b32_e32 v28, v10
	v_mov_b32_e32 v29, v22
	v_pk_fma_f32 v[8:9], v[28:29], v[20:21], v[8:9]
	v_and_b32_e32 v1, 0xffff0000, v1
	v_and_b32_e32 v0, 0xffff0000, v5
	v_mov_b32_e32 v22, v11
	v_pk_fma_f32 v[0:1], v[22:23], v[0:1], v[8:9]
	v_lshlrev_b32_e32 v5, 16, v2
	v_lshlrev_b32_e32 v4, 16, v6
	v_mov_b32_e32 v8, v12
	s_waitcnt lgkmcnt(0)
	v_mov_b32_e32 v9, v24
	v_pk_fma_f32 v[0:1], v[8:9], v[4:5], v[0:1]
	v_and_b32_e32 v5, 0xffff0000, v2
	v_and_b32_e32 v4, 0xffff0000, v6
	v_mov_b32_e32 v24, v13
	v_pk_fma_f32 v[0:1], v[24:25], v[4:5], v[0:1]
	v_lshlrev_b32_e32 v5, 16, v3
	v_lshlrev_b32_e32 v4, 16, v7
	v_mov_b32_e32 v8, v14
	v_mov_b32_e32 v9, v26
	v_pk_fma_f32 v[0:1], v[8:9], v[4:5], v[0:1]
	v_and_b32_e32 v3, 0xffff0000, v3
	v_and_b32_e32 v2, 0xffff0000, v7
	v_mov_b32_e32 v26, v15
	v_pk_fma_f32 v[0:1], v[26:27], v[2:3], v[0:1]
	v_mov_b32_e32 v30, s62
	v_add_f32_e32 v0, v17, v0
	v_add_f32_e32 v17, v0, v1
	global_load_dwordx4 v[0:3], v[18:19], off offset:240
	global_load_dwordx4 v[4:7], v[18:19], off offset:224
	global_load_dwordx4 v[8:11], v[18:19], off offset:208
	global_load_dwordx4 v[12:15], v[18:19], off offset:192
	ds_read_b128 v[18:21], v30
	ds_read_b128 v[22:25], v30 offset:16
	ds_read_b128 v[26:29], v30 offset:32
	ds_read_b128 v[30:33], v30 offset:48
	s_waitcnt lgkmcnt(3)
	v_mov_b32_e32 v36, v18
	s_waitcnt lgkmcnt(1)
	v_mov_b32_e32 v37, v26
	v_mov_b32_e32 v26, v19
	s_waitcnt vmcnt(1)
	v_and_b32_e32 v39, 0xffff0000, v8
	s_waitcnt vmcnt(0)
	v_and_b32_e32 v38, 0xffff0000, v12
	v_lshlrev_b32_e32 v35, 16, v8
	v_lshlrev_b32_e32 v34, 16, v12
	v_pk_mul_f32 v[18:19], v[26:27], v[38:39]
	v_lshlrev_b32_e32 v27, 16, v9
	v_pk_fma_f32 v[18:19], v[36:37], v[34:35], v[18:19]
	v_lshlrev_b32_e32 v26, 16, v13
	v_mov_b32_e32 v34, v20
	v_mov_b32_e32 v35, v28
	v_pk_fma_f32 v[18:19], v[34:35], v[26:27], v[18:19]
	v_and_b32_e32 v9, 0xffff0000, v9
	v_and_b32_e32 v8, 0xffff0000, v13
	v_mov_b32_e32 v28, v21
	v_pk_fma_f32 v[8:9], v[28:29], v[8:9], v[18:19]
	v_lshlrev_b32_e32 v13, 16, v10
	v_lshlrev_b32_e32 v12, 16, v14
	v_mov_b32_e32 v18, v22
	s_waitcnt lgkmcnt(0)
	v_mov_b32_e32 v19, v30
	v_pk_fma_f32 v[8:9], v[18:19], v[12:13], v[8:9]
	v_and_b32_e32 v13, 0xffff0000, v10
	v_and_b32_e32 v12, 0xffff0000, v14
	v_mov_b32_e32 v30, v23
	v_pk_fma_f32 v[8:9], v[30:31], v[12:13], v[8:9]
	v_lshlrev_b32_e32 v13, 16, v11
	v_lshlrev_b32_e32 v12, 16, v15
	v_mov_b32_e32 v18, v24
	v_mov_b32_e32 v19, v32
	v_pk_fma_f32 v[8:9], v[18:19], v[12:13], v[8:9]
	v_and_b32_e32 v11, 0xffff0000, v11
	v_and_b32_e32 v10, 0xffff0000, v15
	v_mov_b32_e32 v32, v25
	v_pk_fma_f32 v[8:9], v[32:33], v[10:11], v[8:9]
	v_mov_b32_e32 v22, s63
	v_add_f32_e32 v8, v17, v8
	v_add_f32_e32 v17, v8, v9
	ds_read_b128 v[8:11], v22
	ds_read_b128 v[12:15], v22 offset:16
	ds_read_b128 v[18:21], v22 offset:32
	ds_read_b128 v[22:25], v22 offset:48
	v_and_b32_e32 v31, 0xffff0000, v0
	v_and_b32_e32 v30, 0xffff0000, v4
	v_lshlrev_b32_e32 v27, 16, v0
	s_waitcnt lgkmcnt(1)
	v_mov_b32_e32 v29, v18
	v_mov_b32_e32 v18, v9
	v_lshlrev_b32_e32 v26, 16, v4
	v_mov_b32_e32 v28, v8
	v_pk_mul_f32 v[8:9], v[18:19], v[30:31]
	v_lshlrev_b32_e32 v19, 16, v1
	v_pk_fma_f32 v[8:9], v[28:29], v[26:27], v[8:9]
	v_lshlrev_b32_e32 v18, 16, v5
	v_mov_b32_e32 v26, v10
	v_mov_b32_e32 v27, v20
	v_pk_fma_f32 v[8:9], v[26:27], v[18:19], v[8:9]
	v_and_b32_e32 v1, 0xffff0000, v1
	v_and_b32_e32 v0, 0xffff0000, v5
	v_mov_b32_e32 v20, v11
	v_pk_fma_f32 v[0:1], v[20:21], v[0:1], v[8:9]
	v_lshlrev_b32_e32 v5, 16, v2
	v_lshlrev_b32_e32 v4, 16, v6
	v_mov_b32_e32 v8, v12
	s_waitcnt lgkmcnt(0)
	v_mov_b32_e32 v9, v22
	v_pk_fma_f32 v[0:1], v[8:9], v[4:5], v[0:1]
	v_and_b32_e32 v5, 0xffff0000, v2
	v_and_b32_e32 v4, 0xffff0000, v6
	v_mov_b32_e32 v22, v13
	v_pk_fma_f32 v[0:1], v[22:23], v[4:5], v[0:1]
	v_lshlrev_b32_e32 v5, 16, v3
	v_lshlrev_b32_e32 v4, 16, v7
	v_mov_b32_e32 v8, v14
	v_mov_b32_e32 v9, v24
	v_pk_fma_f32 v[0:1], v[8:9], v[4:5], v[0:1]
	v_and_b32_e32 v3, 0xffff0000, v3
	v_and_b32_e32 v2, 0xffff0000, v7
	v_mov_b32_e32 v24, v15
	v_pk_fma_f32 v[0:1], v[24:25], v[2:3], v[0:1]
	s_nop 0
	v_add_f32_e32 v0, v17, v0
	v_ashrrev_i32_e32 v17, 31, v16
	v_add_f32_e32 v2, v0, v1
	v_lshl_add_u64 v[0:1], v[16:17], 2, s[40:41]
	global_store_dword v[0:1], v2, off
